# P1 weight convert_tile chains de-serialised (W_out and layer-0 W_in): 16 loads in flight + counted vmcnt waits instead of load/vmcnt(0)/ds_write x16
# speedup vs baseline: 1.0195x; 1.0067x over previous
; __device__ __forceinline__ int otid() { int t = threadIdx.x; asm volatile("" : "+v"(t)); return t; }
; template <bool INPROJ>
; __device__ __forceinline__ void convert_tile(const float* __restrict__ src, int src_ld, int n0, int k0,
;                                              bf16_t* __restrict__ dst, int dst_ld, char* smem) {
;   float* tile = (float*)smem;
;   const int tid = otid();
;   const int nn = tid & 63;
;   int sc = INPROJ ? inproj_src_col(n0 + nn) : (n0 + nn);
; #pragma unroll
;   for (int i = 0; i < 16; ++i) {
;     const int kk = (tid >> 6) + 4 * i;
;     float v = 0.f;
;     if (sc >= 0) v = src[(size_t)(k0 + kk) * src_ld + sc];
;     tile[kk * 65 + nn] = v;
;   }
.LBB0_738:
	s_andn2_b64 vcc, exec, s[26:27]
	s_cbranch_vccnz .LBB0_740
	s_lshl_b32 s18, s30, 2
	s_lshl_b32 s26, s30, 6
	v_mov_b32_e32 v10, v178
	s_and_b32 s18, s18, 0x7fc0
	s_and_b32 s26, s26, 0x3c0
	s_addk_i32 s18, 0x9600
	v_ashrrev_i32_e32 v12, 6, v10
	v_and_b32_e32 v11, 63, v10
	v_add_u32_e32 v6, s26, v12
	v_or_b32_e32 v2, s18, v11
	v_ashrrev_i32_e32 v7, 31, v6
	v_lshl_add_u64 v[4:5], v[2:3], 2, s[24:25]
	v_lshlrev_b64 v[8:9], 12, v[6:7]
	v_lshl_add_u64 v[8:9], v[4:5], 0, v[8:9]
	global_load_dword v144, v[8:9], off
	v_add_u32_e32 v8, 4, v6
	s_movk_i32 s1, 0x104
	v_ashrrev_i32_e32 v9, 31, v8
	v_mul_lo_u32 v7, v12, s1
	v_lshlrev_b64 v[8:9], 12, v[8:9]
	v_lshl_add_u32 v11, v11, 2, v7
	v_lshl_add_u64 v[8:9], v[4:5], 0, v[8:9]
	s_lshl_b32 s26, s26, 1
	v_readlane_b32 s0, v243, 48
	s_add_u32 s26, s0, s26
	v_readlane_b32 s0, v243, 49
	s_addc_u32 s27, s0, 0
	s_mov_b32 s0, 0xffff0000
	s_mov_b32 s73, 0xffff0000
	global_load_dword v145, v[8:9], off
	v_add_u32_e32 v8, 8, v6
	v_ashrrev_i32_e32 v9, 31, v8
	v_lshlrev_b64 v[8:9], 12, v[8:9]
	v_lshl_add_u64 v[8:9], v[4:5], 0, v[8:9]
	global_load_dword v146, v[8:9], off
	v_add_u32_e32 v8, 12, v6
	v_ashrrev_i32_e32 v9, 31, v8
	v_lshlrev_b64 v[8:9], 12, v[8:9]
	v_lshl_add_u64 v[8:9], v[4:5], 0, v[8:9]
	global_load_dword v147, v[8:9], off
	v_add_u32_e32 v8, 16, v6
	v_ashrrev_i32_e32 v9, 31, v8
	v_lshlrev_b64 v[8:9], 12, v[8:9]
	v_lshl_add_u64 v[8:9], v[4:5], 0, v[8:9]
	global_load_dword v148, v[8:9], off
	v_add_u32_e32 v8, 20, v6
	v_ashrrev_i32_e32 v9, 31, v8
	v_lshlrev_b64 v[8:9], 12, v[8:9]
	v_lshl_add_u64 v[8:9], v[4:5], 0, v[8:9]
	global_load_dword v149, v[8:9], off
	v_add_u32_e32 v8, 24, v6
	v_ashrrev_i32_e32 v9, 31, v8
	v_lshlrev_b64 v[8:9], 12, v[8:9]
	v_lshl_add_u64 v[8:9], v[4:5], 0, v[8:9]
	global_load_dword v150, v[8:9], off
	v_add_u32_e32 v8, 28, v6
	v_ashrrev_i32_e32 v9, 31, v8
	v_lshlrev_b64 v[8:9], 12, v[8:9]
	v_lshl_add_u64 v[8:9], v[4:5], 0, v[8:9]
	global_load_dword v151, v[8:9], off
	v_add_u32_e32 v8, 32, v6
	v_ashrrev_i32_e32 v9, 31, v8
	v_lshlrev_b64 v[8:9], 12, v[8:9]
	v_lshl_add_u64 v[8:9], v[4:5], 0, v[8:9]
	global_load_dword v152, v[8:9], off
	v_add_u32_e32 v8, 36, v6
	v_ashrrev_i32_e32 v9, 31, v8
	v_lshlrev_b64 v[8:9], 12, v[8:9]
	v_lshl_add_u64 v[8:9], v[4:5], 0, v[8:9]
	global_load_dword v153, v[8:9], off
	v_add_u32_e32 v8, 40, v6
	v_ashrrev_i32_e32 v9, 31, v8
	v_lshlrev_b64 v[8:9], 12, v[8:9]
	v_lshl_add_u64 v[8:9], v[4:5], 0, v[8:9]
	global_load_dword v154, v[8:9], off
	v_add_u32_e32 v8, 44, v6
	v_ashrrev_i32_e32 v9, 31, v8
	v_lshlrev_b64 v[8:9], 12, v[8:9]
	v_lshl_add_u64 v[8:9], v[4:5], 0, v[8:9]
	global_load_dword v155, v[8:9], off
	v_add_u32_e32 v8, 48, v6
	v_ashrrev_i32_e32 v9, 31, v8
	v_lshlrev_b64 v[8:9], 12, v[8:9]
	v_lshl_add_u64 v[8:9], v[4:5], 0, v[8:9]
	global_load_dword v156, v[8:9], off
	v_add_u32_e32 v8, 52, v6
	v_ashrrev_i32_e32 v9, 31, v8
	v_lshlrev_b64 v[8:9], 12, v[8:9]
	v_lshl_add_u64 v[8:9], v[4:5], 0, v[8:9]
	global_load_dword v157, v[8:9], off
	v_add_u32_e32 v8, 56, v6
	v_ashrrev_i32_e32 v9, 31, v8
	v_lshlrev_b64 v[8:9], 12, v[8:9]
	v_lshl_add_u64 v[8:9], v[4:5], 0, v[8:9]
	v_add_u32_e32 v6, 60, v6
	v_ashrrev_i32_e32 v7, 31, v6
	v_lshlrev_b64 v[6:7], 12, v[6:7]
	v_lshl_add_u64 v[4:5], v[4:5], 0, v[6:7]
	global_load_dword v158, v[8:9], off
	global_load_dword v159, v[4:5], off
	s_waitcnt vmcnt(15)
	ds_write_b32 v11, v144
	s_waitcnt vmcnt(14)
	ds_write_b32 v11, v145 offset:1040
	s_waitcnt vmcnt(13)
	ds_write_b32 v11, v146 offset:2080
	s_waitcnt vmcnt(12)
	ds_write_b32 v11, v147 offset:3120
	s_waitcnt vmcnt(11)
	ds_write_b32 v11, v148 offset:4160
	s_waitcnt vmcnt(10)
	ds_write_b32 v11, v149 offset:5200
	s_waitcnt vmcnt(9)
	ds_write_b32 v11, v150 offset:6240
	s_waitcnt vmcnt(8)
	ds_write_b32 v11, v151 offset:7280
	s_waitcnt vmcnt(7)
	ds_write_b32 v11, v152 offset:8320
	s_waitcnt vmcnt(6)
	ds_write_b32 v11, v153 offset:9360
	s_waitcnt vmcnt(5)
	ds_write_b32 v11, v154 offset:10400
	s_waitcnt vmcnt(4)
	ds_write_b32 v11, v155 offset:11440
	s_waitcnt vmcnt(3)
	ds_write_b32 v11, v156 offset:12480
	s_waitcnt vmcnt(2)
	ds_write_b32 v11, v157 offset:13520
	s_waitcnt vmcnt(1)
	ds_write_b32 v11, v158 offset:14560
	s_waitcnt vmcnt(0)
	ds_write_b32 v11, v159 offset:15600
	v_lshlrev_b32_e32 v2, 1, v10
	v_and_b32_e32 v6, 62, v2
	v_ashrrev_i32_e32 v11, 5, v10
	v_lshlrev_b32_e32 v2, 1, v6
	v_lshl_add_u64 v[4:5], s[26:27], 0, v[2:3]
	v_lshlrev_b32_e32 v2, 2, v11
	v_mad_u32_u24 v2, v6, s1, v2
	s_waitcnt lgkmcnt(0)
	s_barrier
; __device__ __forceinline__ unsigned pack2(float a, float b) { return (unsigned)f2bf(a) | ((unsigned)f2bf(b) << 16); }
; template <bool INPROJ>
; __device__ __forceinline__ void convert_tile(const float* __restrict__ src, int src_ld, int n0, int k0,
;                                              bf16_t* __restrict__ dst, int dst_ld, char* smem) {
;     ...
;   __syncthreads();
; #pragma unroll
;   for (int i = 0; i < 8; ++i) {
;     const int n2 = (tid >> 5) + 8 * i;
;     const int k2 = (tid & 31) * 2;
;     const unsigned pk = pack2(tile[k2 * 65 + n2], tile[(k2 + 1) * 65 + n2]);
;     *(unsigned*)(dst + (size_t)(n0 + n2) * dst_ld + k0 + k2) = pk;
;   }
;   __syncthreads();
	ds_read2_b32 v[6:7], v2 offset0:65 offset1:73
	ds_read2_b32 v[8:9], v2 offset1:8
	s_waitcnt lgkmcnt(0)
	v_bfe_u32 v10, v8, 16, 1
	v_add3_u32 v8, v8, v10, s37
	v_bfe_u32 v10, v6, 16, 1
	v_add3_u32 v6, v6, v10, s37
	v_add_u32_e32 v10, s18, v11
	v_ashrrev_i32_e32 v11, 31, v10
	v_lshrrev_b32_e32 v8, 16, v8
	v_lshlrev_b64 v[12:13], 11, v[10:11]
	v_and_or_b32 v6, v6, s0, v8
	v_lshl_add_u64 v[12:13], v[4:5], 0, v[12:13]
	global_store_dword v[12:13], v6, off
	v_bfe_u32 v6, v9, 16, 1
	v_add3_u32 v6, v9, v6, s37
	v_bfe_u32 v8, v7, 16, 1
	v_lshrrev_b32_e32 v6, 16, v6
	v_add3_u32 v7, v7, v8, s37
	v_and_or_b32 v8, v7, s0, v6
	v_add_u32_e32 v6, 8, v10
	v_ashrrev_i32_e32 v7, 31, v6
	v_lshlrev_b64 v[6:7], 11, v[6:7]
	v_lshl_add_u64 v[6:7], v[4:5], 0, v[6:7]
	global_store_dword v[6:7], v8, off
	ds_read2_b32 v[6:7], v2 offset0:16 offset1:24
	ds_read2_b32 v[8:9], v2 offset0:81 offset1:89
	v_add_u32_e32 v12, 16, v10
	v_ashrrev_i32_e32 v13, 31, v12
	v_lshlrev_b64 v[12:13], 11, v[12:13]
	s_waitcnt lgkmcnt(1)
	v_bfe_u32 v11, v6, 16, 1
	v_add3_u32 v6, v6, v11, s37
	s_waitcnt lgkmcnt(0)
	v_bfe_u32 v11, v8, 16, 1
	v_lshrrev_b32_e32 v6, 16, v6
	v_add3_u32 v8, v8, v11, s37
	v_and_or_b32 v6, v8, s0, v6
	v_lshl_add_u64 v[12:13], v[4:5], 0, v[12:13]
	global_store_dword v[12:13], v6, off
	v_bfe_u32 v6, v7, 16, 1
	v_add3_u32 v6, v7, v6, s37
	v_bfe_u32 v7, v9, 16, 1
	v_lshrrev_b32_e32 v6, 16, v6
	v_add3_u32 v7, v9, v7, s37
	v_and_or_b32 v8, v7, s0, v6
	v_add_u32_e32 v6, 24, v10
	v_ashrrev_i32_e32 v7, 31, v6
	v_lshlrev_b64 v[6:7], 11, v[6:7]
	v_lshl_add_u64 v[6:7], v[4:5], 0, v[6:7]
	global_store_dword v[6:7], v8, off
	ds_read2_b32 v[6:7], v2 offset0:32 offset1:40
	ds_read2_b32 v[8:9], v2 offset0:97 offset1:105
	v_add_u32_e32 v12, 32, v10
	v_ashrrev_i32_e32 v13, 31, v12
	v_lshlrev_b64 v[12:13], 11, v[12:13]
	s_waitcnt lgkmcnt(1)
	v_bfe_u32 v11, v6, 16, 1
	v_add3_u32 v6, v6, v11, s37
	s_waitcnt lgkmcnt(0)
	v_bfe_u32 v11, v8, 16, 1
	v_lshrrev_b32_e32 v6, 16, v6
	v_add3_u32 v8, v8, v11, s37
	v_and_or_b32 v6, v8, s0, v6
	v_lshl_add_u64 v[12:13], v[4:5], 0, v[12:13]
	global_store_dword v[12:13], v6, off
	v_bfe_u32 v6, v7, 16, 1
	v_add3_u32 v6, v7, v6, s37
	v_bfe_u32 v7, v9, 16, 1
	v_lshrrev_b32_e32 v6, 16, v6
	v_add3_u32 v7, v9, v7, s37
	v_and_or_b32 v8, v7, s0, v6
	v_add_u32_e32 v6, 40, v10
	v_ashrrev_i32_e32 v7, 31, v6
	v_lshlrev_b64 v[6:7], 11, v[6:7]
	v_lshl_add_u64 v[6:7], v[4:5], 0, v[6:7]
	global_store_dword v[6:7], v8, off
	ds_read2_b32 v[6:7], v2 offset0:113 offset1:121
	ds_read2_b32 v[8:9], v2 offset0:48 offset1:56
	v_add_u32_e32 v12, 48, v10
	v_ashrrev_i32_e32 v13, 31, v12
	v_lshlrev_b64 v[12:13], 11, v[12:13]
	v_lshl_add_u64 v[12:13], v[4:5], 0, v[12:13]
	s_waitcnt lgkmcnt(0)
	v_bfe_u32 v2, v8, 16, 1
	v_add3_u32 v2, v8, v2, s37
	v_bfe_u32 v8, v6, 16, 1
	v_lshrrev_b32_e32 v2, 16, v2
	v_add3_u32 v6, v6, v8, s37
	v_and_or_b32 v2, v6, s0, v2
	global_store_dword v[12:13], v2, off
	v_bfe_u32 v2, v9, 16, 1
	v_add3_u32 v2, v9, v2, s37
	v_bfe_u32 v6, v7, 16, 1
	v_lshrrev_b32_e32 v2, 16, v2
	v_add3_u32 v6, v7, v6, s37
	v_and_or_b32 v2, v6, s0, v2
	v_add_u32_e32 v6, 56, v10
	v_ashrrev_i32_e32 v7, 31, v6
	v_lshlrev_b64 v[6:7], 11, v[6:7]
	v_lshl_add_u64 v[4:5], v[4:5], 0, v[6:7]
	global_store_dword v[4:5], v2, off
	s_barrier

; __device__ __forceinline__ int otid() { int t = threadIdx.x; asm volatile("" : "+v"(t)); return t; }
; template <bool INPROJ>
; __device__ __forceinline__ void convert_tile(const float* __restrict__ src, int src_ld, int n0, int k0,
;                                              bf16_t* __restrict__ dst, int dst_ld, char* smem) {
;     ...
;   const int tid = otid();
;   const int nn = tid & 63;
;   int sc = INPROJ ? inproj_src_col(n0 + nn) : (n0 + nn);
; #pragma unroll
;   for (int i = 0; i < 16; ++i) {
;     const int kk = (tid >> 6) + 4 * i;
;     float v = 0.f;
;     if (sc >= 0) v = src[(size_t)(k0 + kk) * src_ld + sc];
;     tile[kk * 65 + nn] = v;
;   }
.LBB0_776:
	v_readlane_b32 s40, v244, 34
	s_lshl_b32 s26, s30, 6
	v_readlane_b32 s44, v244, 38
	v_readlane_b32 s45, v244, 39
	s_and_b32 s28, s26, 0x3c0
	v_ashrrev_i32_e32 v7, 6, v6
	v_cmp_lt_i32_e32 vcc, -1, v2
	v_lshl_add_u64 v[4:5], v[2:3], 2, s[44:45]
	v_mov_b32_e32 v9, 0
	v_mov_b32_e32 v10, 0
	v_readlane_b32 s41, v244, 35
	v_readlane_b32 s42, v244, 36
	v_readlane_b32 s43, v244, 37
	v_readlane_b32 s46, v244, 40
	v_readlane_b32 s47, v244, 41
	v_mov_b32_e32 v144, 0
	v_mov_b32_e32 v145, 0
	v_mov_b32_e32 v146, 0
	v_mov_b32_e32 v147, 0
	v_mov_b32_e32 v148, 0
	v_mov_b32_e32 v149, 0
	v_mov_b32_e32 v150, 0
	v_mov_b32_e32 v151, 0
	v_mov_b32_e32 v152, 0
	v_mov_b32_e32 v153, 0
	v_mov_b32_e32 v154, 0
	v_mov_b32_e32 v155, 0
	v_mov_b32_e32 v156, 0
	v_mov_b32_e32 v157, 0
	v_mov_b32_e32 v158, 0
	v_mov_b32_e32 v159, 0
	s_and_saveexec_b64 s[26:27], vcc
	s_cbranch_execz .Lcvp1_skip
	s_mov_b32 s0, 0x8a40
	v_add_u32_e32 v160, s28, v7
	v_mad_i64_i32 v[162:163], s[38:39], v160, s0, v[4:5]
	global_load_dword v144, v[162:163], off
	v_add3_u32 v160, v7, s28, 4
	v_mad_i64_i32 v[162:163], s[38:39], v160, s0, v[4:5]
	global_load_dword v145, v[162:163], off
	v_add3_u32 v160, v7, s28, 8
	v_mad_i64_i32 v[162:163], s[38:39], v160, s0, v[4:5]
	global_load_dword v146, v[162:163], off
	v_add3_u32 v160, v7, s28, 12
	v_mad_i64_i32 v[162:163], s[38:39], v160, s0, v[4:5]
	global_load_dword v147, v[162:163], off
	v_add3_u32 v160, v7, s28, 16
	v_mad_i64_i32 v[162:163], s[38:39], v160, s0, v[4:5]
	global_load_dword v148, v[162:163], off
	v_add3_u32 v160, v7, s28, 20
	v_mad_i64_i32 v[162:163], s[38:39], v160, s0, v[4:5]
	global_load_dword v149, v[162:163], off
	v_add3_u32 v160, v7, s28, 24
	v_mad_i64_i32 v[162:163], s[38:39], v160, s0, v[4:5]
	global_load_dword v150, v[162:163], off
	v_add3_u32 v160, v7, s28, 28
	v_mad_i64_i32 v[162:163], s[38:39], v160, s0, v[4:5]
	global_load_dword v151, v[162:163], off
	v_add3_u32 v160, v7, s28, 32
	v_mad_i64_i32 v[162:163], s[38:39], v160, s0, v[4:5]
	global_load_dword v152, v[162:163], off
	v_add3_u32 v160, v7, s28, 36
	v_mad_i64_i32 v[162:163], s[38:39], v160, s0, v[4:5]
	global_load_dword v153, v[162:163], off
	v_add3_u32 v160, v7, s28, 40
	v_mad_i64_i32 v[162:163], s[38:39], v160, s0, v[4:5]
	global_load_dword v154, v[162:163], off
	v_add3_u32 v160, v7, s28, 44
	v_mad_i64_i32 v[162:163], s[38:39], v160, s0, v[4:5]
	global_load_dword v155, v[162:163], off
	v_add3_u32 v160, v7, s28, 48
	v_mad_i64_i32 v[162:163], s[38:39], v160, s0, v[4:5]
	global_load_dword v156, v[162:163], off
	v_add3_u32 v160, v7, s28, 52
	v_mad_i64_i32 v[162:163], s[38:39], v160, s0, v[4:5]
	global_load_dword v157, v[162:163], off
	v_add3_u32 v160, v7, s28, 56
	v_mad_i64_i32 v[162:163], s[38:39], v160, s0, v[4:5]
	global_load_dword v158, v[162:163], off
	v_add3_u32 v160, v7, s28, 60
	v_mad_i64_i32 v[162:163], s[38:39], v160, s0, v[4:5]
	global_load_dword v159, v[162:163], off
; __device__ __forceinline__ unsigned pack2(float a, float b) { return (unsigned)f2bf(a) | ((unsigned)f2bf(b) << 16); }
; template <bool INPROJ>
; __device__ __forceinline__ void convert_tile(const float* __restrict__ src, int src_ld, int n0, int k0,
;                                              bf16_t* __restrict__ dst, int dst_ld, char* smem) {
;     ...
; #pragma unroll
;   for (int i = 0; i < 16; ++i) {
;     const int kk = (tid >> 6) + 4 * i;
;     float v = 0.f;
;     if (sc >= 0) v = src[(size_t)(k0 + kk) * src_ld + sc];
;     tile[kk * 65 + nn] = v;
;   }
;   __syncthreads();
; #pragma unroll
;   for (int i = 0; i < 8; ++i) {
;     const int n2 = (tid >> 5) + 8 * i;
;     const int k2 = (tid & 31) * 2;
;     const unsigned pk = pack2(tile[k2 * 65 + n2], tile[(k2 + 1) * 65 + n2]);
;     *(unsigned*)(dst + (size_t)(n0 + n2) * dst_ld + k0 + k2) = pk;
;   }
;   __syncthreads();
.Lcvp1_skip:
	s_or_b64 exec, exec, s[26:27]
	s_movk_i32 s0, 0x104
	v_lshlrev_b32_e32 v2, 2, v8
	v_mul_lo_u32 v8, v7, s0
	v_add_u32_e32 v2, v2, v8
	s_waitcnt vmcnt(15)
	ds_write_b32 v2, v144
	s_waitcnt vmcnt(14)
	ds_write_b32 v2, v145 offset:1040
	s_waitcnt vmcnt(13)
	ds_write_b32 v2, v146 offset:2080
	s_waitcnt vmcnt(12)
	ds_write_b32 v2, v147 offset:3120
	s_waitcnt vmcnt(11)
	ds_write_b32 v2, v148 offset:4160
	s_waitcnt vmcnt(10)
	ds_write_b32 v2, v149 offset:5200
	s_waitcnt vmcnt(9)
	ds_write_b32 v2, v150 offset:6240
	s_waitcnt vmcnt(8)
	ds_write_b32 v2, v151 offset:7280
	s_waitcnt vmcnt(7)
	ds_write_b32 v2, v152 offset:8320
	s_waitcnt vmcnt(6)
	ds_write_b32 v2, v153 offset:9360
	s_waitcnt vmcnt(5)
	ds_write_b32 v2, v154 offset:10400
	s_waitcnt vmcnt(4)
	ds_write_b32 v2, v155 offset:11440
	s_waitcnt vmcnt(3)
	ds_write_b32 v2, v156 offset:12480
	s_waitcnt vmcnt(2)
	ds_write_b32 v2, v157 offset:13520
	s_waitcnt vmcnt(1)
	ds_write_b32 v2, v158 offset:14560
	s_waitcnt vmcnt(0)
	ds_write_b32 v2, v159 offset:15600
	v_ashrrev_i32_e32 v10, 5, v6
	v_lshlrev_b32_e32 v2, 1, v6
	s_lshl_b32 s26, s28, 1
	v_readlane_b32 s0, v244, 42
	v_and_b32_e32 v2, 62, v2
	s_add_u32 s26, s0, s26
	v_lshlrev_b32_e32 v4, 2, v10
	s_movk_i32 s0, 0x104
	v_mad_u32_u24 v14, v2, s0, v4
	s_waitcnt lgkmcnt(0)
	s_barrier
	ds_read2_b32 v[4:5], v14 offset1:8
	ds_read2_b32 v[6:7], v14 offset0:65 offset1:73
	v_readlane_b32 s0, v244, 43
	s_addc_u32 s27, s0, 0
	v_lshlrev_b32_e32 v2, 1, v2
	v_lshl_add_u64 v[8:9], s[26:27], 0, v[2:3]
	s_waitcnt lgkmcnt(1)
	v_bfe_u32 v2, v4, 16, 1
	v_add_u32_e32 v10, s18, v10
	v_add3_u32 v2, v4, v2, s37
	s_waitcnt lgkmcnt(0)
	v_bfe_u32 v4, v6, 16, 1
	v_ashrrev_i32_e32 v11, 31, v10
	v_lshrrev_b32_e32 v2, 16, v2
	v_add3_u32 v4, v6, v4, s37
	s_mov_b32 s0, 0xffff0000
	v_lshlrev_b64 v[12:13], 11, v[10:11]
	v_and_or_b32 v2, v4, s0, v2
	v_lshl_add_u64 v[12:13], v[8:9], 0, v[12:13]
	global_store_dword v[12:13], v2, off
	v_bfe_u32 v2, v5, 16, 1
	v_add3_u32 v2, v5, v2, s37
	v_bfe_u32 v4, v7, 16, 1
	v_lshrrev_b32_e32 v2, 16, v2
	v_add3_u32 v4, v7, v4, s37
	ds_read2_b32 v[6:7], v14 offset0:16 offset1:24
	v_and_or_b32 v2, v4, s0, v2
	v_add_u32_e32 v4, 8, v10
	ds_read2_b32 v[12:13], v14 offset0:81 offset1:89
	v_ashrrev_i32_e32 v5, 31, v4
	v_lshlrev_b64 v[4:5], 11, v[4:5]
	v_lshl_add_u64 v[4:5], v[8:9], 0, v[4:5]
	global_store_dword v[4:5], v2, off
	s_waitcnt lgkmcnt(1)
	v_bfe_u32 v2, v6, 16, 1
	v_add3_u32 v2, v6, v2, s37
	s_waitcnt lgkmcnt(0)
	v_bfe_u32 v4, v12, 16, 1
	v_lshrrev_b32_e32 v2, 16, v2
	v_add3_u32 v4, v12, v4, s37
	v_and_or_b32 v2, v4, s0, v2
	v_add_u32_e32 v4, 16, v10
	v_ashrrev_i32_e32 v5, 31, v4
	v_lshlrev_b64 v[4:5], 11, v[4:5]
	v_lshl_add_u64 v[4:5], v[8:9], 0, v[4:5]
	global_store_dword v[4:5], v2, off
	v_bfe_u32 v2, v7, 16, 1
	v_add3_u32 v2, v7, v2, s37
	v_bfe_u32 v4, v13, 16, 1
	v_lshrrev_b32_e32 v2, 16, v2
	v_add3_u32 v4, v13, v4, s37
	ds_read2_b32 v[6:7], v14 offset0:32 offset1:40
	v_and_or_b32 v2, v4, s0, v2
	v_add_u32_e32 v4, 24, v10
	ds_read2_b32 v[12:13], v14 offset0:97 offset1:105
	v_ashrrev_i32_e32 v5, 31, v4
	v_lshlrev_b64 v[4:5], 11, v[4:5]
	v_lshl_add_u64 v[4:5], v[8:9], 0, v[4:5]
	global_store_dword v[4:5], v2, off
	s_waitcnt lgkmcnt(1)
	v_bfe_u32 v2, v6, 16, 1
	v_add3_u32 v2, v6, v2, s37
	s_waitcnt lgkmcnt(0)
	v_bfe_u32 v4, v12, 16, 1
	v_lshrrev_b32_e32 v2, 16, v2
	v_add3_u32 v4, v12, v4, s37
	v_and_or_b32 v2, v4, s0, v2
	v_add_u32_e32 v4, 32, v10
	v_ashrrev_i32_e32 v5, 31, v4
	v_lshlrev_b64 v[4:5], 11, v[4:5]
	v_lshl_add_u64 v[4:5], v[8:9], 0, v[4:5]
	global_store_dword v[4:5], v2, off
	v_bfe_u32 v2, v7, 16, 1
	v_add3_u32 v2, v7, v2, s37
	v_bfe_u32 v4, v13, 16, 1
	v_lshrrev_b32_e32 v2, 16, v2
	v_add3_u32 v4, v13, v4, s37
	ds_read2_b32 v[6:7], v14 offset0:48 offset1:56
	v_and_or_b32 v2, v4, s0, v2
	v_add_u32_e32 v4, 40, v10
	ds_read2_b32 v[12:13], v14 offset0:113 offset1:121
	v_ashrrev_i32_e32 v5, 31, v4
	v_lshlrev_b64 v[4:5], 11, v[4:5]
	v_lshl_add_u64 v[4:5], v[8:9], 0, v[4:5]
	global_store_dword v[4:5], v2, off
	s_waitcnt lgkmcnt(1)
	v_bfe_u32 v2, v6, 16, 1
	v_add3_u32 v2, v6, v2, s37
	s_waitcnt lgkmcnt(0)
	v_bfe_u32 v4, v12, 16, 1
	v_lshrrev_b32_e32 v2, 16, v2
	v_add3_u32 v4, v12, v4, s37
	v_and_or_b32 v2, v4, s0, v2
	v_add_u32_e32 v4, 48, v10
	v_ashrrev_i32_e32 v5, 31, v4
	v_lshlrev_b64 v[4:5], 11, v[4:5]
	v_lshl_add_u64 v[4:5], v[8:9], 0, v[4:5]
	global_store_dword v[4:5], v2, off
	v_bfe_u32 v2, v7, 16, 1
	v_add3_u32 v2, v7, v2, s37
	v_bfe_u32 v4, v13, 16, 1
	v_lshrrev_b32_e32 v2, 16, v2
	v_add3_u32 v4, v13, v4, s37
	v_and_or_b32 v2, v4, s0, v2
	v_add_u32_e32 v4, 56, v10
	v_ashrrev_i32_e32 v5, 31, v4
	v_lshlrev_b64 v[4:5], 11, v[4:5]
	s_mov_b32 s73, 0xffff0000
	v_lshl_add_u64 v[4:5], v[8:9], 0, v[4:5]
	global_store_dword v[4:5], v2, off
	s_barrier
